# t12 + P5 PV waves: first 8 transposed V reads issued together with the P reads at the step top (fragment register sets swapped)
# baseline (speedup 1.0000x reference)
; #define SBAR() __builtin_amdgcn_sched_barrier(0)
; #define RS_BAR() do { asm volatile("s_waitcnt lgkmcnt(0)" ::: "memory"); __builtin_amdgcn_s_barrier(); asm volatile("" ::: "memory"); } while (0)
; #define VM0() asm volatile("s_waitcnt vmcnt(0)" ::: "memory")
; #define VM0() asm volatile("s_waitcnt vmcnt(0)" ::: "memory")
; #define VMMA(OD, F) do { OD = __builtin_amdgcn_mfma_f32_32x32x16_bf16(pa0, PKF(F[0], F[1]), OD, 0, 0, 0); OD = __builtin_amdgcn_mfma_f32_32x32x16_bf16(pa1, PKF(F[2], F[3]), OD, 0, 0, 0); \
;       OD = __builtin_amdgcn_mfma_f32_32x32x16_bf16(pa2, PKF(F[4], F[5]), OD, 0, 0, 0); OD = __builtin_amdgcn_mfma_f32_32x32x16_bf16(pa3, PKF(F[6], F[7]), OD, 0, 0, 0); } while (0)
; #define LW(n) do { asm volatile("s_waitcnt lgkmcnt(" #n ")" ::: "memory"); SBAR(); } while (0)
; template <class Epi>
; __device__ __forceinline__ void attn_rs_body(const bf16* __restrict__ Qb, const bf16* __restrict__ Kc, const bf16* __restrict__ V0c, const bf16* __restrict__ V1c, int NT, char* lds, const Epi& epi) {
;     ...
;       const int vb = vb0 + b * 32768;
;       s16x4 fa[8], fb[8];
;       { const int tv = j < NT ? j : NT - 1; VDMA(tv, b ^ 1); }
;       asm volatile("s_waitcnt lgkmcnt(0)" ::: "memory"); SBAR();
;       VRD(fa, 0, 0); VRD(fb, 1, 0); LW(8); VMMA(o[0], fa);
;       VRD(fa, 2, 0); LW(8); VMMA(o[1], fb);
;       VRD(fb, 3, 0); LW(8); VMMA(o[2], fa);
;       VRD(fa, 0, 1); LW(8); VMMA(o[3], fb);
;       VRD(fb, 1, 1); LW(8); VMMA(o[4], fa);
;       VRD(fa, 2, 1); LW(8); VMMA(o[5], fb);
;       VRD(fb, 3, 1); LW(8); VMMA(o[6], fa);
;       LW(0); VMMA(o[7], fb);
;       VM0(); RS_BAR();
;     }
.LBB0_500:
	s_lshl_b32 s72, s72, 15
	v_lshl_add_u64 v[244:245], v[176:177], 0, s[48:49]
	s_add_i32 s72, s51, s72
	v_lshl_add_u64 v[246:247], v[174:175], 0, s[48:49]
	v_lshl_add_u32 v0, s71, 15, v182
	ds_read_b64_tr_b16 v[146:147], v0 offset:0x200
	ds_read_b64_tr_b16 v[148:149], v0 offset:0xa00
	ds_read_b64_tr_b16 v[150:151], v0 offset:0x1200
	ds_read_b64_tr_b16 v[152:153], v0 offset:0x1a00
	ds_read_b64_tr_b16 v[154:155], v0 offset:0x2200
	ds_read_b64_tr_b16 v[156:157], v0 offset:0x2a00
	ds_read_b64_tr_b16 v[158:159], v0 offset:0x3200
	ds_read_b64_tr_b16 v[160:161], v0 offset:0x3a00
	s_add_i32 m0, s72, 0x8000
	v_lshl_add_u64 v[248:249], v[244:245], 0, s[12:13]
	global_load_lds_dwordx4 v[248:249], off
	s_add_i32 m0, s72, 0xc000
	v_lshl_add_u64 v[250:251], v[244:245], 0, s[14:15]
	global_load_lds_dwordx4 v[250:251], off
	s_waitcnt lgkmcnt(8)
	s_nop 0
	v_mfma_f32_32x32x16_bf16 v[114:129], v[142:145], v[184:187], v[114:129]
	ds_read_b64_tr_b16 v[184:185], v0 offset:0x400
	ds_read_b64_tr_b16 v[186:187], v0 offset:0xc00
	v_mfma_f32_32x32x16_bf16 v[114:129], v[138:141], v[188:191], v[114:129]
	ds_read_b64_tr_b16 v[188:189], v0 offset:0x1400
	ds_read_b64_tr_b16 v[190:191], v0 offset:0x1c00
	s_add_i32 m0, s72, 0x8400
	v_lshl_add_u64 v[248:249], v[244:245], 0, s[16:17]
	global_load_lds_dwordx4 v[248:249], off
	v_mfma_f32_32x32x16_bf16 v[114:129], v[134:137], v[192:195], v[114:129]
	ds_read_b64_tr_b16 v[192:193], v0 offset:0x2400
	ds_read_b64_tr_b16 v[194:195], v0 offset:0x2c00
	v_mfma_f32_32x32x16_bf16 v[114:129], v[130:133], v[196:199], v[114:129]
	ds_read_b64_tr_b16 v[196:197], v0 offset:0x3400
	ds_read_b64_tr_b16 v[198:199], v0 offset:0x3c00
	s_waitcnt lgkmcnt(8)
	s_add_i32 m0, s72, 0xc400
	v_lshl_add_u64 v[250:251], v[244:245], 0, s[18:19]
	global_load_lds_dwordx4 v[250:251], off
	v_mfma_f32_32x32x16_bf16 v[98:113], v[142:145], v[146:149], v[98:113]
	ds_read_b64_tr_b16 v[146:147], v0 offset:0x600
	ds_read_b64_tr_b16 v[148:149], v0 offset:0xe00
	v_mfma_f32_32x32x16_bf16 v[98:113], v[138:141], v[150:153], v[98:113]
	ds_read_b64_tr_b16 v[150:151], v0 offset:0x1600
	ds_read_b64_tr_b16 v[152:153], v0 offset:0x1e00
	s_add_i32 m0, s72, 0x8800
	v_lshl_add_u64 v[248:249], v[246:247], 0, s[12:13]
	global_load_lds_dwordx4 v[248:249], off
	v_mfma_f32_32x32x16_bf16 v[98:113], v[134:137], v[154:157], v[98:113]
	ds_read_b64_tr_b16 v[154:155], v0 offset:0x2600
	ds_read_b64_tr_b16 v[156:157], v0 offset:0x2e00
	v_mfma_f32_32x32x16_bf16 v[98:113], v[130:133], v[158:161], v[98:113]
	ds_read_b64_tr_b16 v[158:159], v0 offset:0x3600
	ds_read_b64_tr_b16 v[160:161], v0 offset:0x3e00
	s_waitcnt lgkmcnt(8)
	s_add_i32 m0, s72, 0xc800
	v_lshl_add_u64 v[250:251], v[246:247], 0, s[14:15]
	global_load_lds_dwordx4 v[250:251], off
	v_mfma_f32_32x32x16_bf16 v[82:97], v[142:145], v[184:187], v[82:97]
	ds_read_b64_tr_b16 v[184:185], v0 offset:0x4000
	ds_read_b64_tr_b16 v[186:187], v0 offset:0x4800
	v_mfma_f32_32x32x16_bf16 v[82:97], v[138:141], v[188:191], v[82:97]
	ds_read_b64_tr_b16 v[188:189], v0 offset:0x5000
	ds_read_b64_tr_b16 v[190:191], v0 offset:0x5800
	s_add_i32 m0, s72, 0x8c00
	v_lshl_add_u64 v[248:249], v[246:247], 0, s[16:17]
	global_load_lds_dwordx4 v[248:249], off
	v_mfma_f32_32x32x16_bf16 v[82:97], v[134:137], v[192:195], v[82:97]
	ds_read_b64_tr_b16 v[192:193], v0 offset:0x6000
	ds_read_b64_tr_b16 v[194:195], v0 offset:0x6800
	v_mfma_f32_32x32x16_bf16 v[82:97], v[130:133], v[196:199], v[82:97]
	ds_read_b64_tr_b16 v[196:197], v0 offset:0x7000
	ds_read_b64_tr_b16 v[198:199], v0 offset:0x7800
	s_waitcnt lgkmcnt(8)
	s_add_i32 m0, s72, 0xcc00
	v_lshl_add_u64 v[250:251], v[246:247], 0, s[18:19]
	global_load_lds_dwordx4 v[250:251], off
	v_mfma_f32_32x32x16_bf16 v[66:81], v[142:145], v[146:149], v[66:81]
	ds_read_b64_tr_b16 v[146:147], v0 offset:0x4200
	ds_read_b64_tr_b16 v[148:149], v0 offset:0x4a00
	v_mfma_f32_32x32x16_bf16 v[66:81], v[138:141], v[150:153], v[66:81]
	ds_read_b64_tr_b16 v[150:151], v0 offset:0x5200
	ds_read_b64_tr_b16 v[152:153], v0 offset:0x5a00
	v_mfma_f32_32x32x16_bf16 v[66:81], v[134:137], v[154:157], v[66:81]
	ds_read_b64_tr_b16 v[154:155], v0 offset:0x6200
	ds_read_b64_tr_b16 v[156:157], v0 offset:0x6a00
	v_mfma_f32_32x32x16_bf16 v[66:81], v[130:133], v[158:161], v[66:81]
	ds_read_b64_tr_b16 v[158:159], v0 offset:0x7200
	ds_read_b64_tr_b16 v[160:161], v0 offset:0x7a00
	s_waitcnt lgkmcnt(8)
	v_mfma_f32_32x32x16_bf16 v[50:65], v[142:145], v[184:187], v[50:65]
	ds_read_b64_tr_b16 v[184:185], v0 offset:0x4400
	ds_read_b64_tr_b16 v[186:187], v0 offset:0x4c00
	v_mfma_f32_32x32x16_bf16 v[50:65], v[138:141], v[188:191], v[50:65]
	ds_read_b64_tr_b16 v[188:189], v0 offset:0x5400
	ds_read_b64_tr_b16 v[190:191], v0 offset:0x5c00
	v_mfma_f32_32x32x16_bf16 v[50:65], v[134:137], v[192:195], v[50:65]
	ds_read_b64_tr_b16 v[192:193], v0 offset:0x6400
	ds_read_b64_tr_b16 v[194:195], v0 offset:0x6c00
	v_mfma_f32_32x32x16_bf16 v[50:65], v[130:133], v[196:199], v[50:65]
	ds_read_b64_tr_b16 v[196:197], v0 offset:0x7400
	ds_read_b64_tr_b16 v[198:199], v0 offset:0x7c00
	s_waitcnt lgkmcnt(8)
	v_mfma_f32_32x32x16_bf16 v[34:49], v[142:145], v[146:149], v[34:49]
	ds_read_b64_tr_b16 v[146:147], v0 offset:0x4600
	ds_read_b64_tr_b16 v[148:149], v0 offset:0x4e00
	v_mfma_f32_32x32x16_bf16 v[34:49], v[138:141], v[150:153], v[34:49]
	ds_read_b64_tr_b16 v[150:151], v0 offset:0x5600
	ds_read_b64_tr_b16 v[152:153], v0 offset:0x5e00
	v_mfma_f32_32x32x16_bf16 v[34:49], v[134:137], v[154:157], v[34:49]
	ds_read_b64_tr_b16 v[154:155], v0 offset:0x6600
	ds_read_b64_tr_b16 v[156:157], v0 offset:0x6e00
	v_mfma_f32_32x32x16_bf16 v[34:49], v[130:133], v[158:161], v[34:49]
	ds_read_b64_tr_b16 v[158:159], v0 offset:0x7600
	ds_read_b64_tr_b16 v[160:161], v0 offset:0x7e00
	s_waitcnt lgkmcnt(8)
	s_waitcnt lgkmcnt(0)
	s_waitcnt vmcnt(0)
	s_add_i32 s70, s70, 1
	s_waitcnt lgkmcnt(0)
	s_barrier
	s_add_u32 s48, s48, 0x4000
	s_addc_u32 s49, s49, 0
	v_mfma_f32_32x32x16_bf16 v[18:33], v[142:145], v[184:187], v[18:33]
	v_mfma_f32_32x32x16_bf16 v[2:17], v[142:145], v[146:149], v[2:17]
	v_mfma_f32_32x32x16_bf16 v[18:33], v[138:141], v[188:191], v[18:33]
	v_mfma_f32_32x32x16_bf16 v[2:17], v[138:141], v[150:153], v[2:17]
	v_mfma_f32_32x32x16_bf16 v[18:33], v[134:137], v[192:195], v[18:33]
	v_mfma_f32_32x32x16_bf16 v[2:17], v[134:137], v[154:157], v[2:17]
	s_cmp_eq_u32 s48, 0x1fc000
	v_mfma_f32_32x32x16_bf16 v[18:33], v[130:133], v[196:199], v[18:33]
	v_mfma_f32_32x32x16_bf16 v[2:17], v[130:133], v[158:161], v[2:17]
	s_cbranch_scc1 .LBB0_503
; #define SBAR() __builtin_amdgcn_sched_barrier(0)
; __device__ __forceinline__ int crow(int r, int hi) { return (r & 3) + 8 * (r >> 2) + 4 * hi; }
; #define VMMA(OD, F) do { OD = __builtin_amdgcn_mfma_f32_32x32x16_bf16(pa0, PKF(F[0], F[1]), OD, 0, 0, 0); OD = __builtin_amdgcn_mfma_f32_32x32x16_bf16(pa1, PKF(F[2], F[3]), OD, 0, 0, 0); \
;       OD = __builtin_amdgcn_mfma_f32_32x32x16_bf16(pa2, PKF(F[4], F[5]), OD, 0, 0, 0); OD = __builtin_amdgcn_mfma_f32_32x32x16_bf16(pa3, PKF(F[6], F[7]), OD, 0, 0, 0); } while (0)
; #define LW(n) do { asm volatile("s_waitcnt lgkmcnt(" #n ")" ::: "memory"); SBAR(); } while (0)
; template <class Epi>
; __device__ __forceinline__ void attn_rs_body(const bf16* __restrict__ Qb, const bf16* __restrict__ Kc, const bf16* __restrict__ V0c, const bf16* __restrict__ V1c, int NT, char* lds, const Epi& epi) {
;     ...
;     for (int j = 1; j <= NT; ++j) {
;       const int b = (j - 1) & 1;
;       const char* Pb = Pl + b * 16384;
;       const bf16x8 pa0 = *(const bf16x8*)(Pb), pa1 = *(const bf16x8*)(Pb + 1024), pa2 = *(const bf16x8*)(Pb + 2048), pa3 = *(const bf16x8*)(Pb + 3072);
;       const float flag = al[b * 256 + 32];
;       if (__builtin_amdgcn_readfirstlane(__float_as_uint(flag)) != 0u) {
;         float av[16];
; #pragma unroll
;         for (int r = 0; r < 16; ++r) av[r] = al[b * 256 + crow(r, hi)];
; #pragma unroll
;         for (int d = 0; d < 8; ++d)
; #pragma unroll
;           for (int r = 0; r < 16; ++r) o[d][r] *= av[r];
;       }
;       const int vb = vb0 + b * 32768;
;       s16x4 fa[8], fb[8];
;       { const int tv = j < NT ? j : NT - 1; VDMA(tv, b ^ 1); }
;       asm volatile("s_waitcnt lgkmcnt(0)" ::: "memory"); SBAR();
;       VRD(fa, 0, 0); VRD(fb, 1, 0); LW(8); VMMA(o[0], fa);
.LBB0_501:
	s_and_b32 s72, s70, 1
	s_xor_b32 s71, s72, 1
	s_lshl_b32 s73, s71, 10
	s_add_i32 s73, s65, s73
	v_mov_b32_e32 v130, s73
	v_lshl_add_u32 v0, s71, 14, v179
	v_lshl_add_u32 v252, s71, 15, v182
	ds_read_b32 v146, v130 offset:128
	ds_read_b128 v[142:145], v0
	ds_read_b128 v[138:141], v0 offset:1024
	ds_read_b128 v[134:137], v0 offset:2048
	ds_read_b128 v[130:133], v0 offset:3072
	ds_read_b64_tr_b16 v[184:185], v252 offset:0
	ds_read_b64_tr_b16 v[186:187], v252 offset:0x800
	ds_read_b64_tr_b16 v[188:189], v252 offset:0x1000
	ds_read_b64_tr_b16 v[190:191], v252 offset:0x1800
	ds_read_b64_tr_b16 v[192:193], v252 offset:0x2000
	ds_read_b64_tr_b16 v[194:195], v252 offset:0x2800
	ds_read_b64_tr_b16 v[196:197], v252 offset:0x3000
	ds_read_b64_tr_b16 v[198:199], v252 offset:0x3800
	s_waitcnt lgkmcnt(8)
	v_readfirstlane_b32 s74, v146
	s_cmp_eq_u32 s74, 0
	s_cbranch_scc1 .LBB0_500
	v_add_u32_e32 v0, s73, v164
	ds_read_b128 v[158:161], v0 offset:96
	ds_read_b128 v[154:157], v0 offset:64
	ds_read_b128 v[150:153], v0 offset:32
	ds_read_b128 v[146:149], v0
	s_waitcnt lgkmcnt(0)
	v_pk_mul_f32 v[126:127], v[126:127], v[158:159]
	v_pk_mul_f32 v[122:123], v[122:123], v[154:155]
	v_pk_mul_f32 v[118:119], v[118:119], v[150:151]
	v_pk_mul_f32 v[128:129], v[128:129], v[160:161]
	v_pk_mul_f32 v[124:125], v[124:125], v[156:157]
	v_pk_mul_f32 v[120:121], v[120:121], v[152:153]
	v_pk_mul_f32 v[116:117], v[116:117], v[148:149]
	v_pk_mul_f32 v[114:115], v[114:115], v[146:147]
	v_pk_mul_f32 v[110:111], v[110:111], v[158:159]
	v_pk_mul_f32 v[106:107], v[106:107], v[154:155]
	v_pk_mul_f32 v[102:103], v[102:103], v[150:151]
	v_pk_mul_f32 v[112:113], v[112:113], v[160:161]
	v_pk_mul_f32 v[108:109], v[108:109], v[156:157]
	v_pk_mul_f32 v[104:105], v[104:105], v[152:153]
	v_pk_mul_f32 v[100:101], v[100:101], v[148:149]
	v_pk_mul_f32 v[98:99], v[98:99], v[146:147]
	v_pk_mul_f32 v[94:95], v[94:95], v[158:159]
	v_pk_mul_f32 v[90:91], v[90:91], v[154:155]
	v_pk_mul_f32 v[86:87], v[86:87], v[150:151]
	v_pk_mul_f32 v[96:97], v[96:97], v[160:161]
	v_pk_mul_f32 v[92:93], v[92:93], v[156:157]
	v_pk_mul_f32 v[88:89], v[88:89], v[152:153]
	v_pk_mul_f32 v[84:85], v[84:85], v[148:149]
	v_pk_mul_f32 v[82:83], v[82:83], v[146:147]
	v_pk_mul_f32 v[78:79], v[78:79], v[158:159]
	v_pk_mul_f32 v[74:75], v[74:75], v[154:155]
	v_pk_mul_f32 v[70:71], v[70:71], v[150:151]
	v_pk_mul_f32 v[80:81], v[80:81], v[160:161]
	v_pk_mul_f32 v[76:77], v[76:77], v[156:157]
	v_pk_mul_f32 v[72:73], v[72:73], v[152:153]
	v_pk_mul_f32 v[68:69], v[68:69], v[148:149]
	v_pk_mul_f32 v[66:67], v[66:67], v[146:147]
	v_pk_mul_f32 v[62:63], v[62:63], v[158:159]
	v_pk_mul_f32 v[58:59], v[58:59], v[154:155]
	v_pk_mul_f32 v[54:55], v[54:55], v[150:151]
	v_pk_mul_f32 v[64:65], v[64:65], v[160:161]
	v_pk_mul_f32 v[60:61], v[60:61], v[156:157]
	v_pk_mul_f32 v[56:57], v[56:57], v[152:153]
	v_pk_mul_f32 v[52:53], v[52:53], v[148:149]
	v_pk_mul_f32 v[50:51], v[50:51], v[146:147]
	v_pk_mul_f32 v[46:47], v[46:47], v[158:159]
	v_pk_mul_f32 v[42:43], v[42:43], v[154:155]
	v_pk_mul_f32 v[38:39], v[38:39], v[150:151]
	v_pk_mul_f32 v[48:49], v[48:49], v[160:161]
	v_pk_mul_f32 v[44:45], v[44:45], v[156:157]
	v_pk_mul_f32 v[40:41], v[40:41], v[152:153]
	v_pk_mul_f32 v[36:37], v[36:37], v[148:149]
	v_pk_mul_f32 v[34:35], v[34:35], v[146:147]
	v_pk_mul_f32 v[30:31], v[30:31], v[158:159]
	v_pk_mul_f32 v[26:27], v[26:27], v[154:155]
	v_pk_mul_f32 v[22:23], v[22:23], v[150:151]
	v_pk_mul_f32 v[32:33], v[32:33], v[160:161]
	v_pk_mul_f32 v[28:29], v[28:29], v[156:157]
	v_pk_mul_f32 v[24:25], v[24:25], v[152:153]
	v_pk_mul_f32 v[20:21], v[20:21], v[148:149]
	v_pk_mul_f32 v[18:19], v[18:19], v[146:147]
	v_pk_mul_f32 v[14:15], v[14:15], v[158:159]
	v_pk_mul_f32 v[10:11], v[10:11], v[154:155]
	v_pk_mul_f32 v[6:7], v[6:7], v[150:151]
	v_pk_mul_f32 v[16:17], v[16:17], v[160:161]
	v_pk_mul_f32 v[12:13], v[12:13], v[156:157]
	v_pk_mul_f32 v[8:9], v[8:9], v[152:153]
	v_pk_mul_f32 v[4:5], v[4:5], v[148:149]
	v_pk_mul_f32 v[2:3], v[2:3], v[146:147]
	s_branch .LBB0_500
